# v52 + P0 cached-K copies: the three 16-byte loads of a thread issued together (fast path for the 256-workgroup grid) instead of one serial round trip per loop iteration
# speedup vs baseline: 1.0031x; 1.0031x over previous
.LBB0_1895:
	s_or_b64 exec, exec, s[26:27]
	s_load_dwordx2 s[4:5], s[8:9], 0x20
	s_cmp_lg_u32 s16, 0x20000
	s_cbranch_scc1 .Lck_orig
	s_load_dwordx2 s[26:27], s[8:9], 0x10
	v_lshl_add_u64 v[6:7], v[4:5], 3, s[10:11]
	s_mov_b64 s[6:7], exec
	s_waitcnt lgkmcnt(0)
	v_lshl_add_u64 v[8:9], v[4:5], 4, s[26:27]
	v_lshl_add_u64 v[14:15], v[4:5], 4, s[4:5]
	s_mov_b64 s[8:9], 0x200000
	s_and_b64 exec, s[6:7], s[38:39]
	global_load_dwordx4 v[10:13], v[8:9], off
	s_mov_b64 exec, s[6:7]
	global_load_dwordx4 v[16:19], v[14:15], off
	v_lshl_add_u64 v[14:15], v[14:15], 0, s[8:9]
	global_load_dwordx4 v[20:23], v[14:15], off
	s_mov_b64 s[8:9], 0x300000
	v_lshl_add_u64 v[8:9], v[6:7], 0, s[8:9]
	s_mov_b64 s[8:9], 0x400000
	v_lshl_add_u64 v[6:7], v[6:7], 0, s[8:9]
	s_mov_b64 s[8:9], 0x100000
	v_lshl_add_u64 v[14:15], v[6:7], 0, s[8:9]
	s_waitcnt vmcnt(2)
	s_and_b64 exec, s[6:7], s[38:39]
	v_cvt_pk_bf16_f32 v10, v10, v11
	v_cvt_pk_bf16_f32 v11, v12, v13
	global_store_dwordx2 v[8:9], v[10:11], off
	s_mov_b64 exec, s[6:7]
	s_waitcnt vmcnt(1)
	v_cvt_pk_bf16_f32 v16, v16, v17
	v_cvt_pk_bf16_f32 v17, v18, v19
	global_store_dwordx2 v[6:7], v[16:17], off
	s_waitcnt vmcnt(1)
	v_cvt_pk_bf16_f32 v20, v20, v21
	v_cvt_pk_bf16_f32 v21, v22, v23
	global_store_dwordx2 v[14:15], v[20:21], off
	s_branch .LBB0_1901
.Lck_orig:
	s_and_saveexec_b64 s[6:7], s[38:39]
	s_cbranch_execz .LBB0_1898
	s_load_dwordx2 s[26:27], s[8:9], 0x10
	v_lshl_add_u64 v[6:7], v[4:5], 3, s[10:11]
	s_ashr_i32 s17, s16, 31
	s_mov_b64 s[8:9], 0x300000
	v_lshl_add_u64 v[6:7], v[6:7], 0, s[8:9]
	s_lshl_b64 s[8:9], s[16:17], 3
	s_waitcnt lgkmcnt(0)
	v_lshl_add_u64 v[8:9], v[4:5], 4, s[26:27]
	s_lshl_b64 s[26:27], s[16:17], 4
	s_mov_b64 s[38:39], 0
	v_mov_b32_e32 v2, v4
